# owner runs 3 unclaimed phaseA passes
# baseline (speedup 1.0000x reference)
;     ...
; #pragma unroll 1
;     for (int pass = 0; pass * NWAVE < NU; ++pass) {
;         const int unit = pass * NWAVE + wave;
;         const bool active = unit < NU;
;         const int ucl = active ? unit : NU - 1;
;         const u32x4* bp = Bw + (size_t)(ucl * NT) * 64 + lane;
;         const size_t kstr = (size_t)NU * NT * 64;
.LBB0_822:
	s_or_b64 exec, exec, s[8:9]
	s_add_i32 s88, s88, 1
	s_cmp_lt_u32 s88, 3
	s_cbranch_scc1 .Lm3a_go
	v_readlane_b32 s10, v252, 10
	v_readlane_b32 s11, v252, 11
	s_lshl_b32 s6, s90, 2
	s_add_u32 s6, s6, s31
	s_lshl_b32 s6, s6, 3
	s_add_u32 s10, s10, s6
	s_addc_u32 s11, s11, 0

;     ...
; #pragma unroll 1
;     for (int pass = 0; pass * NWAVE < NU; ++pass) {
;         const int unit = pass * NWAVE + wave;
;         const bool active = unit < NU;
;         const int ucl = active ? unit : NU - 1;
.Lm3a_c_w:
	s_barrier
	ds_read_b32 v3, v2
	s_waitcnt lgkmcnt(0)
	v_readfirstlane_b32 s88, v3
	s_nop 3
	s_add_u32 s88, s88, 3
	s_cmp_ge_u32 s88, 9
	s_cbranch_scc1 .LBB0_781

;     ...
; #pragma unroll 1
;     for (int pass = 0; pass * NWAVE < NU; ++pass) {
;         const int unit = pass * NWAVE + wave;
;         const bool active = unit < NU;
;         const int ucl = active ? unit : NU - 1;
.Lha_c_w:
	s_barrier
	ds_read_b32 v3, v2
	s_waitcnt lgkmcnt(0)
	v_readfirstlane_b32 s88, v3
	s_nop 3
	s_add_u32 s88, s88, 3
	s_cmp_ge_u32 s88, 9
	s_cbranch_scc1 .Lha_next
	s_lshl_b32 s2, s88, 3
	v_add_u32_e32 v232, s2, v223
